# v15 + dynamic part of the attention queue split over 4 interleaved counters with stealing
# baseline (speedup 1.0000x reference)
; __device__ __forceinline__ void phase_attn(const Params& p, LAS unsigned char* lds, unsigned* queue) {
;     ...
;         if (tid == 0) *tick = __hip_atomic_fetch_add(queue, 1u, __ATOMIC_RELAXED, __HIP_MEMORY_SCOPE_AGENT);
;         __syncthreads();
;         const int idx = (int)*tick;
.Lq_dyn:
	s_and_b32 s98, s2, 3
	s_mov_b32 s99, 0
	v_readlane_b32 s0, v255, 6
	v_readlane_b32 s1, v255, 7
.Lq_retry:
	s_lshl_b32 s100, s98, 8
	v_mov_b32_e32 v252, s100
	v_mov_b32_e32 v4, 1
	s_nop 4
	global_atomic_add v4, v252, v4, s[0:1] sc0
	s_waitcnt vmcnt(0)
	v_readfirstlane_b32 s101, v4
	s_lshl_b32 s101, s101, 2
	s_add_i32 s101, s101, s98
	s_addk_i32 s101, 0x100
	s_cmpk_lt_u32 s101, 0x200
	s_cbranch_scc1 .Lq_ok
	s_add_i32 s98, s98, 1
	s_and_b32 s98, s98, 3
	s_add_i32 s99, s99, 1
	s_cmpk_lt_u32 s99, 4
	s_cbranch_scc1 .Lq_retry
	s_movk_i32 s101, 0x200
.Lq_ok:
	v_mov_b32_e32 v4, s101
